# accumulate-chain MFMA order extended to the pool GEMM k-loop (last GEMM site still in hipcc order)
# speedup vs baseline: 1.0120x; 1.0092x over previous
; #define PG8_STAGE(bufoff, gbase, voff) do { _Pragma("unroll") for (int _i = 0; _i < 2; ++_i) \
;         __builtin_amdgcn_global_load_lds((const unsigned*)((const char*)(gbase) + (voff)[_i]), (LAS unsigned*)(lds + (bufoff) + ldsw + _i * 8192), 16, 0, 0); } while (0)
; #define PG8_LDA(dst, b, h) do { _Pragma("unroll") for (int m = 0; m < 4; ++m) _Pragma("unroll") for (int k = 0; k < 2; ++k) dst[m][k] = *(const LAS bf16x8*)(lds + PG8_SA(b, h) + aoff + m * 2048 + k * 1024); } while (0)
; #define PG8_LDB(dst, b, h) do { _Pragma("unroll") for (int n = 0; n < 2; ++n) _Pragma("unroll") for (int k = 0; k < 2; ++k) dst[n][k] = *(const LAS bf16x8*)(lds + PG8_SB(b, h) + boff + n * 2048 + k * 1024); } while (0)
; #define PG8_MMA(ai, bj, At, Bt) do { __builtin_amdgcn_s_setprio(1); _Pragma("unroll") for (int m = 0; m < 4; ++m) _Pragma("unroll") for (int n = 0; n < 2; ++n) _Pragma("unroll") for (int k = 0; k < 2; ++k) \
;         acc[ai][bj][m][n] = __builtin_amdgcn_mfma_f32_16x16x32_bf16(Bt[n][k], At[m][k], acc[ai][bj][m][n], 0, 0, 0); __builtin_amdgcn_s_setprio(0); } while (0)
; #define PG8_WAIT_V(n) asm volatile("s_waitcnt vmcnt(" #n ")" ::: "memory")
; #define PG8_WAIT_L(n) asm volatile("s_waitcnt lgkmcnt(" #n ")" ::: "memory")
; #define PG8_BAR __builtin_amdgcn_s_barrier()
; #define PG8_SCHED __builtin_amdgcn_sched_barrier(0)
; template <class EpiT>
; __device__ __forceinline__ void gemm_phase(LAS unsigned char* lds, const Gemm g, const StaticOrder& S, const EpiT& E) {
;     ...
;             const char* a1 = cA + (size_t)(t + 1) * kstep;
;             const char* a2 = last ? nA : cA + (size_t)(t + 2) * kstep; const char* b2 = last ? nB : cB + (size_t)(t + 2) * kstep;
;             const char* a3 = a2 + kstep; const char* b3 = b2 + kstep;
;             PG8_LDB(B0, 0, 0); PG8_LDB(B1, 0, 1); PG8_SCHED; PG8_LDA(At, 0, 0); PG8_STAGE(PG8_SA(1, 1), a1 + hstepA, voffA);
;             PG8_WAIT_V(8); PG8_WAIT_L(0); PG8_BAR; PG8_MMA(0, 0, At, B0); PG8_MMA(0, 1, At, B1); PG8_BAR; PG8_SCHED;
;             PG8_LDA(At, 0, 1); PG8_STAGE(PG8_SB(0, 0), b2, voffB); PG8_STAGE(PG8_SB(0, 1), b2 + hstepB, voffB); PG8_STAGE(PG8_SA(0, 0), a2, voffA);
;             PG8_WAIT_V(8); PG8_WAIT_L(0); PG8_BAR; PG8_MMA(1, 0, At, B0); PG8_MMA(1, 1, At, B1); PG8_BAR; PG8_SCHED;
.LBB0_296:
	s_add_u32 s58, s66, s54
	s_addc_u32 s59, s67, 0
	s_add_u32 s55, s58, 0x100
	s_addc_u32 s61, s59, 0
	s_and_b64 s[56:57], s[68:69], exec
	s_cselect_b32 s73, s21, s61
	s_cselect_b32 s72, s20, s55
	s_add_u32 s54, s46, s54
	s_addc_u32 s55, s47, 0
	s_add_u32 s56, s54, 0x100
	s_addc_u32 s57, s55, 0
	s_and_b64 s[54:55], s[68:69], exec
	s_cselect_b32 s75, s17, s57
	s_cselect_b32 s74, s19, s56
	s_add_u32 s78, s58, 0x40080
	s_addc_u32 s79, s59, 0
	s_add_i32 s80, s51, s36
	ds_read_b128 v[128:131], v167
	ds_read_b128 v[132:135], v167 offset:1024
	ds_read_b128 v[136:139], v167 offset:2048
	ds_read_b128 v[140:143], v167 offset:3072
	ds_read_b128 v[160:163], v169
	ds_read_b128 v[172:175], v169 offset:1024
	ds_read_b128 v[176:179], v169 offset:2048
	ds_read_b128 v[180:183], v169 offset:3072
	s_add_i32 m0, s37, 0xc000
	s_add_i32 s84, s37, 0xe000
	s_add_i32 s61, s80, 0x2000
	s_add_u32 s76, s74, 0x10000
	s_addc_u32 s77, s75, 0
	s_add_i32 s65, s52, s36
	s_add_i32 s64, s65, 0x2000
	s_add_i32 s59, 0, 0x18000
	s_add_i32 s58, 0, 0x1c000
	s_add_u32 s70, s72, 0x40000
	s_addc_u32 s71, s73, 0
	s_add_i32 s57, s59, s36
	s_add_i32 s55, s57, 0x2000
	s_add_u32 s68, s74, 0x10080
	s_addc_u32 s69, s75, 0
	s_add_i32 s56, s58, s36
	s_add_i32 s54, s56, 0x2000
	v_lshl_add_u64 v[216:217], s[78:79], 0, v[146:147]
	ds_read_b128 v[184:187], v170
	ds_read_b128 v[188:191], v170 offset:1024
	ds_read_b128 v[192:195], v170 offset:2048
	ds_read_b128 v[196:199], v170 offset:3072
	ds_read_b128 v[200:203], v170 offset:4096
	ds_read_b128 v[204:207], v170 offset:5120
	ds_read_b128 v[208:211], v170 offset:6144
	ds_read_b128 v[212:215], v170 offset:7168
	global_load_lds_dwordx4 v[216:217], off
	v_lshl_add_u64 v[216:217], s[78:79], 0, v[150:151]
	s_mov_b32 m0, s84
	s_nop 0
	global_load_lds_dwordx4 v[216:217], off
	s_waitcnt vmcnt(8)
	s_waitcnt lgkmcnt(0)
	s_barrier
	s_setprio 1
	s_waitcnt lgkmcnt(0)
	v_mfma_f32_16x16x32_bf16 v[124:127], v[128:131], v[184:187], v[124:127]
	v_mfma_f32_16x16x32_bf16 v[124:127], v[132:135], v[188:191], v[124:127]
	v_mfma_f32_16x16x32_bf16 v[108:111], v[128:131], v[192:195], v[108:111]
	v_mfma_f32_16x16x32_bf16 v[108:111], v[132:135], v[196:199], v[108:111]
	v_mfma_f32_16x16x32_bf16 v[92:95], v[128:131], v[200:203], v[92:95]
	v_mfma_f32_16x16x32_bf16 v[92:95], v[132:135], v[204:207], v[92:95]
	v_mfma_f32_16x16x32_bf16 v[76:79], v[128:131], v[208:211], v[76:79]
	v_mfma_f32_16x16x32_bf16 v[76:79], v[132:135], v[212:215], v[76:79]
	v_mfma_f32_16x16x32_bf16 v[120:123], v[136:139], v[184:187], v[120:123]
	v_mfma_f32_16x16x32_bf16 v[120:123], v[140:143], v[188:191], v[120:123]
	v_mfma_f32_16x16x32_bf16 v[104:107], v[136:139], v[192:195], v[104:107]
	v_mfma_f32_16x16x32_bf16 v[104:107], v[140:143], v[196:199], v[104:107]
	v_mfma_f32_16x16x32_bf16 v[88:91], v[136:139], v[200:203], v[88:91]
	v_mfma_f32_16x16x32_bf16 v[88:91], v[140:143], v[204:207], v[88:91]
	v_mfma_f32_16x16x32_bf16 v[72:75], v[136:139], v[208:211], v[72:75]
	v_mfma_f32_16x16x32_bf16 v[72:75], v[140:143], v[212:215], v[72:75]
	s_setprio 0
	s_setprio 1
	v_mfma_f32_16x16x32_bf16 v[116:119], v[160:163], v[184:187], v[116:119]
	v_mfma_f32_16x16x32_bf16 v[116:119], v[172:175], v[188:191], v[116:119]
	v_mfma_f32_16x16x32_bf16 v[100:103], v[160:163], v[192:195], v[100:103]
	v_mfma_f32_16x16x32_bf16 v[100:103], v[172:175], v[196:199], v[100:103]
	v_mfma_f32_16x16x32_bf16 v[84:87], v[160:163], v[200:203], v[84:87]
	v_mfma_f32_16x16x32_bf16 v[84:87], v[172:175], v[204:207], v[84:87]
	v_mfma_f32_16x16x32_bf16 v[68:71], v[160:163], v[208:211], v[68:71]
	v_mfma_f32_16x16x32_bf16 v[68:71], v[172:175], v[212:215], v[68:71]
	v_mfma_f32_16x16x32_bf16 v[112:115], v[176:179], v[184:187], v[112:115]
	v_mfma_f32_16x16x32_bf16 v[112:115], v[180:183], v[188:191], v[112:115]
	v_mfma_f32_16x16x32_bf16 v[96:99], v[176:179], v[192:195], v[96:99]
	v_mfma_f32_16x16x32_bf16 v[96:99], v[180:183], v[196:199], v[96:99]
	v_mfma_f32_16x16x32_bf16 v[80:83], v[176:179], v[200:203], v[80:83]
	v_mfma_f32_16x16x32_bf16 v[80:83], v[180:183], v[204:207], v[80:83]
	v_mfma_f32_16x16x32_bf16 v[64:67], v[176:179], v[208:211], v[64:67]
	v_mfma_f32_16x16x32_bf16 v[64:67], v[180:183], v[212:215], v[64:67]
	s_setprio 0
	s_barrier
	s_mov_b32 m0, s80
	v_lshl_add_u64 v[216:217], s[74:75], 0, v[148:149]
	ds_read_b128 v[184:187], v170 offset:16384
	ds_read_b128 v[188:191], v170 offset:17408
	ds_read_b128 v[192:195], v170 offset:18432
	ds_read_b128 v[196:199], v170 offset:19456
	ds_read_b128 v[200:203], v170 offset:20480
	ds_read_b128 v[204:207], v170 offset:21504
	ds_read_b128 v[208:211], v170 offset:22528
	ds_read_b128 v[212:215], v170 offset:23552
	global_load_lds_dwordx4 v[216:217], off
	v_lshl_add_u64 v[218:219], s[74:75], 0, v[152:153]
	s_mov_b32 m0, s61
	v_lshl_add_u64 v[220:221], s[76:77], 0, v[148:149]
	global_load_lds_dwordx4 v[218:219], off
	s_mov_b32 m0, s65
	v_lshl_add_u64 v[222:223], s[72:73], 0, v[150:151]
	global_load_lds_dwordx4 v[220:221], off
	v_lshl_add_u64 v[220:221], s[76:77], 0, v[152:153]
	s_mov_b32 m0, s64
	s_nop 0
	global_load_lds_dwordx4 v[220:221], off
	v_lshl_add_u64 v[220:221], s[72:73], 0, v[146:147]
	s_mov_b32 m0, s37
	s_nop 0
	global_load_lds_dwordx4 v[220:221], off
	s_mov_b32 m0, s38
	s_nop 0
	global_load_lds_dwordx4 v[222:223], off
	s_waitcnt vmcnt(8)
	s_waitcnt lgkmcnt(0)
	s_barrier
; #define PG8_STAGE(bufoff, gbase, voff) do { _Pragma("unroll") for (int _i = 0; _i < 2; ++_i) \
;         __builtin_amdgcn_global_load_lds((const unsigned*)((const char*)(gbase) + (voff)[_i]), (LAS unsigned*)(lds + (bufoff) + ldsw + _i * 8192), 16, 0, 0); } while (0)
; #define PG8_LDA(dst, b, h) do { _Pragma("unroll") for (int m = 0; m < 4; ++m) _Pragma("unroll") for (int k = 0; k < 2; ++k) dst[m][k] = *(const LAS bf16x8*)(lds + PG8_SA(b, h) + aoff + m * 2048 + k * 1024); } while (0)
; #define PG8_LDB(dst, b, h) do { _Pragma("unroll") for (int n = 0; n < 2; ++n) _Pragma("unroll") for (int k = 0; k < 2; ++k) dst[n][k] = *(const LAS bf16x8*)(lds + PG8_SB(b, h) + boff + n * 2048 + k * 1024); } while (0)
; #define PG8_MMA(ai, bj, At, Bt) do { __builtin_amdgcn_s_setprio(1); _Pragma("unroll") for (int m = 0; m < 4; ++m) _Pragma("unroll") for (int n = 0; n < 2; ++n) _Pragma("unroll") for (int k = 0; k < 2; ++k) \
;         acc[ai][bj][m][n] = __builtin_amdgcn_mfma_f32_16x16x32_bf16(Bt[n][k], At[m][k], acc[ai][bj][m][n], 0, 0, 0); __builtin_amdgcn_s_setprio(0); } while (0)
; #define PG8_WAIT_V(n) asm volatile("s_waitcnt vmcnt(" #n ")" ::: "memory")
; #define PG8_WAIT_L(n) asm volatile("s_waitcnt lgkmcnt(" #n ")" ::: "memory")
; #define PG8_BAR __builtin_amdgcn_s_barrier()
; #define PG8_SCHED __builtin_amdgcn_sched_barrier(0)
; template <class EpiT>
; __device__ __forceinline__ void gemm_phase(LAS unsigned char* lds, const Gemm g, const StaticOrder& S, const EpiT& E) {
;     ...
;             PG8_WAIT_V(8); PG8_WAIT_L(0); PG8_BAR; PG8_MMA(1, 0, At, B0); PG8_MMA(1, 1, At, B1); PG8_BAR; PG8_SCHED;
;             PG8_LDB(B0, 1, 0); PG8_LDB(B1, 1, 1); PG8_SCHED; PG8_LDA(At, 1, 0); PG8_STAGE(PG8_SA(0, 1), a2 + hstepA, voffA);
;             PG8_WAIT_V(8); PG8_WAIT_L(0); PG8_BAR; PG8_MMA(0, 0, At, B0); PG8_MMA(0, 1, At, B1); PG8_BAR; PG8_SCHED;
	s_setprio 1
	s_waitcnt lgkmcnt(0)
	v_mfma_f32_16x16x32_bf16 v[60:63], v[128:131], v[184:187], v[60:63]
	v_mfma_f32_16x16x32_bf16 v[60:63], v[132:135], v[188:191], v[60:63]
	v_mfma_f32_16x16x32_bf16 v[44:47], v[128:131], v[192:195], v[44:47]
	v_mfma_f32_16x16x32_bf16 v[44:47], v[132:135], v[196:199], v[44:47]
	v_mfma_f32_16x16x32_bf16 v[28:31], v[128:131], v[200:203], v[28:31]
	v_mfma_f32_16x16x32_bf16 v[28:31], v[132:135], v[204:207], v[28:31]
	v_mfma_f32_16x16x32_bf16 v[12:15], v[128:131], v[208:211], v[12:15]
	v_mfma_f32_16x16x32_bf16 v[12:15], v[132:135], v[212:215], v[12:15]
	v_mfma_f32_16x16x32_bf16 v[56:59], v[136:139], v[184:187], v[56:59]
	v_mfma_f32_16x16x32_bf16 v[56:59], v[140:143], v[188:191], v[56:59]
	v_mfma_f32_16x16x32_bf16 v[40:43], v[136:139], v[192:195], v[40:43]
	v_mfma_f32_16x16x32_bf16 v[40:43], v[140:143], v[196:199], v[40:43]
	v_mfma_f32_16x16x32_bf16 v[24:27], v[136:139], v[200:203], v[24:27]
	v_mfma_f32_16x16x32_bf16 v[24:27], v[140:143], v[204:207], v[24:27]
	v_mfma_f32_16x16x32_bf16 v[8:11], v[136:139], v[208:211], v[8:11]
	v_mfma_f32_16x16x32_bf16 v[8:11], v[140:143], v[212:215], v[8:11]
	s_setprio 0
	s_setprio 1
	v_mfma_f32_16x16x32_bf16 v[52:55], v[160:163], v[184:187], v[52:55]
	v_mfma_f32_16x16x32_bf16 v[52:55], v[172:175], v[188:191], v[52:55]
	v_mfma_f32_16x16x32_bf16 v[36:39], v[160:163], v[192:195], v[36:39]
	v_mfma_f32_16x16x32_bf16 v[36:39], v[172:175], v[196:199], v[36:39]
	v_mfma_f32_16x16x32_bf16 v[20:23], v[160:163], v[200:203], v[20:23]
	v_mfma_f32_16x16x32_bf16 v[20:23], v[172:175], v[204:207], v[20:23]
	v_mfma_f32_16x16x32_bf16 v[4:7], v[160:163], v[208:211], v[4:7]
	v_mfma_f32_16x16x32_bf16 v[4:7], v[172:175], v[212:215], v[4:7]
	v_mfma_f32_16x16x32_bf16 v[48:51], v[176:179], v[184:187], v[48:51]
	v_mfma_f32_16x16x32_bf16 v[48:51], v[180:183], v[188:191], v[48:51]
	v_mfma_f32_16x16x32_bf16 v[32:35], v[176:179], v[192:195], v[32:35]
	v_mfma_f32_16x16x32_bf16 v[32:35], v[180:183], v[196:199], v[32:35]
	v_mfma_f32_16x16x32_bf16 v[16:19], v[176:179], v[200:203], v[16:19]
	v_mfma_f32_16x16x32_bf16 v[16:19], v[180:183], v[204:207], v[16:19]
	v_mfma_f32_16x16x32_bf16 v[0:3], v[176:179], v[208:211], v[0:3]
	v_mfma_f32_16x16x32_bf16 v[0:3], v[180:183], v[212:215], v[0:3]
	s_setprio 0
	s_barrier
	v_add_u32_e32 v140, s59, v145
	v_add_u32_e32 v180, s58, v145
	ds_read_b128 v[128:131], v140
	ds_read_b128 v[132:135], v140 offset:1024
	ds_read_b128 v[136:139], v140 offset:2048
	ds_read_b128 v[140:143], v140 offset:3072
	ds_read_b128 v[160:163], v180
	ds_read_b128 v[172:175], v180 offset:1024
	ds_read_b128 v[176:179], v180 offset:2048
	ds_read_b128 v[180:183], v180 offset:3072
	s_mov_b32 m0, s39
	v_lshl_add_u64 v[224:225], s[70:71], 0, v[146:147]
	ds_read_b128 v[184:187], v170 offset:32768
	ds_read_b128 v[188:191], v170 offset:33792
	ds_read_b128 v[192:195], v170 offset:34816
	ds_read_b128 v[196:199], v170 offset:35840
	ds_read_b128 v[200:203], v170 offset:36864
	ds_read_b128 v[204:207], v170 offset:37888
	ds_read_b128 v[208:211], v170 offset:38912
	ds_read_b128 v[212:215], v170 offset:39936
	global_load_lds_dwordx4 v[224:225], off
	v_lshl_add_u64 v[224:225], s[70:71], 0, v[150:151]
	s_mov_b32 m0, s41
	s_nop 0
	global_load_lds_dwordx4 v[224:225], off
	s_waitcnt vmcnt(8)
	s_waitcnt lgkmcnt(0)
	s_barrier
	s_setprio 1
	s_waitcnt lgkmcnt(0)
	v_mfma_f32_16x16x32_bf16 v[124:127], v[128:131], v[184:187], v[124:127]
	v_mfma_f32_16x16x32_bf16 v[124:127], v[132:135], v[188:191], v[124:127]
	v_mfma_f32_16x16x32_bf16 v[108:111], v[128:131], v[192:195], v[108:111]
	v_mfma_f32_16x16x32_bf16 v[108:111], v[132:135], v[196:199], v[108:111]
	v_mfma_f32_16x16x32_bf16 v[92:95], v[128:131], v[200:203], v[92:95]
	v_mfma_f32_16x16x32_bf16 v[92:95], v[132:135], v[204:207], v[92:95]
	v_mfma_f32_16x16x32_bf16 v[76:79], v[128:131], v[208:211], v[76:79]
	v_mfma_f32_16x16x32_bf16 v[76:79], v[132:135], v[212:215], v[76:79]
	v_mfma_f32_16x16x32_bf16 v[120:123], v[136:139], v[184:187], v[120:123]
	v_mfma_f32_16x16x32_bf16 v[120:123], v[140:143], v[188:191], v[120:123]
	v_mfma_f32_16x16x32_bf16 v[104:107], v[136:139], v[192:195], v[104:107]
	v_mfma_f32_16x16x32_bf16 v[104:107], v[140:143], v[196:199], v[104:107]
	v_mfma_f32_16x16x32_bf16 v[88:91], v[136:139], v[200:203], v[88:91]
	v_mfma_f32_16x16x32_bf16 v[88:91], v[140:143], v[204:207], v[88:91]
	v_mfma_f32_16x16x32_bf16 v[72:75], v[136:139], v[208:211], v[72:75]
	v_mfma_f32_16x16x32_bf16 v[72:75], v[140:143], v[212:215], v[72:75]
	s_setprio 0
	s_setprio 1
	v_mfma_f32_16x16x32_bf16 v[116:119], v[160:163], v[184:187], v[116:119]
	v_mfma_f32_16x16x32_bf16 v[116:119], v[172:175], v[188:191], v[116:119]
	v_mfma_f32_16x16x32_bf16 v[100:103], v[160:163], v[192:195], v[100:103]
	v_mfma_f32_16x16x32_bf16 v[100:103], v[172:175], v[196:199], v[100:103]
	v_mfma_f32_16x16x32_bf16 v[84:87], v[160:163], v[200:203], v[84:87]
	v_mfma_f32_16x16x32_bf16 v[84:87], v[172:175], v[204:207], v[84:87]
	v_mfma_f32_16x16x32_bf16 v[68:71], v[160:163], v[208:211], v[68:71]
	v_mfma_f32_16x16x32_bf16 v[68:71], v[172:175], v[212:215], v[68:71]
	v_mfma_f32_16x16x32_bf16 v[112:115], v[176:179], v[184:187], v[112:115]
	v_mfma_f32_16x16x32_bf16 v[112:115], v[180:183], v[188:191], v[112:115]
	v_mfma_f32_16x16x32_bf16 v[96:99], v[176:179], v[192:195], v[96:99]
	v_mfma_f32_16x16x32_bf16 v[96:99], v[180:183], v[196:199], v[96:99]
	v_mfma_f32_16x16x32_bf16 v[80:83], v[176:179], v[200:203], v[80:83]
	v_mfma_f32_16x16x32_bf16 v[80:83], v[180:183], v[204:207], v[80:83]
	v_mfma_f32_16x16x32_bf16 v[64:67], v[176:179], v[208:211], v[64:67]
	v_mfma_f32_16x16x32_bf16 v[64:67], v[180:183], v[212:215], v[64:67]
	s_setprio 0
	s_barrier
; #define PG8_STAGE(bufoff, gbase, voff) do { _Pragma("unroll") for (int _i = 0; _i < 2; ++_i) \
;         __builtin_amdgcn_global_load_lds((const unsigned*)((const char*)(gbase) + (voff)[_i]), (LAS unsigned*)(lds + (bufoff) + ldsw + _i * 8192), 16, 0, 0); } while (0)
; #define PG8_LDA(dst, b, h) do { _Pragma("unroll") for (int m = 0; m < 4; ++m) _Pragma("unroll") for (int k = 0; k < 2; ++k) dst[m][k] = *(const LAS bf16x8*)(lds + PG8_SA(b, h) + aoff + m * 2048 + k * 1024); } while (0)
; #define PG8_MMA(ai, bj, At, Bt) do { __builtin_amdgcn_s_setprio(1); _Pragma("unroll") for (int m = 0; m < 4; ++m) _Pragma("unroll") for (int n = 0; n < 2; ++n) _Pragma("unroll") for (int k = 0; k < 2; ++k) \
;         acc[ai][bj][m][n] = __builtin_amdgcn_mfma_f32_16x16x32_bf16(Bt[n][k], At[m][k], acc[ai][bj][m][n], 0, 0, 0); __builtin_amdgcn_s_setprio(0); } while (0)
; #define PG8_WAIT_V(n) asm volatile("s_waitcnt vmcnt(" #n ")" ::: "memory")
; #define PG8_WAIT_L(n) asm volatile("s_waitcnt lgkmcnt(" #n ")" ::: "memory")
; #define PG8_BAR __builtin_amdgcn_s_barrier()
; #define PG8_SCHED __builtin_amdgcn_sched_barrier(0)
; template <class EpiT>
; __device__ __forceinline__ void gemm_phase(LAS unsigned char* lds, const Gemm g, const StaticOrder& S, const EpiT& E) {
;     ...
;             PG8_LDA(At, 1, 1); PG8_STAGE(PG8_SB(1, 0), b3, voffB); PG8_STAGE(PG8_SB(1, 1), b3 + hstepB, voffB); PG8_STAGE(PG8_SA(1, 0), a3, voffA);
;             PG8_WAIT_V(8); PG8_WAIT_L(0); PG8_BAR; PG8_MMA(1, 0, At, B0); PG8_MMA(1, 1, At, B1); PG8_BAR; PG8_SCHED;
;         }
;         if (wr == 0) PG8_BAR;
	s_mov_b32 m0, s57
	v_lshl_add_u64 v[216:217], v[216:217], 0, s[10:11]
	ds_read_b128 v[184:187], v170 offset:49152
	ds_read_b128 v[188:191], v170 offset:50176
	ds_read_b128 v[192:195], v170 offset:51200
	ds_read_b128 v[196:199], v170 offset:52224
	ds_read_b128 v[200:203], v170 offset:53248
	ds_read_b128 v[204:207], v170 offset:54272
	ds_read_b128 v[208:211], v170 offset:55296
	ds_read_b128 v[212:215], v170 offset:56320
	global_load_lds_dwordx4 v[216:217], off
	v_lshl_add_u64 v[216:217], v[218:219], 0, s[10:11]
	s_mov_b32 m0, s55
	s_nop 0
	global_load_lds_dwordx4 v[216:217], off
	v_lshl_add_u64 v[216:217], s[68:69], 0, v[148:149]
	s_mov_b32 m0, s56
	s_nop 0
	global_load_lds_dwordx4 v[216:217], off
	v_lshl_add_u64 v[216:217], s[68:69], 0, v[152:153]
	s_mov_b32 m0, s54
	s_nop 0
	global_load_lds_dwordx4 v[216:217], off
	v_lshl_add_u64 v[216:217], v[220:221], 0, s[10:11]
	s_mov_b32 m0, s44
	s_nop 0
	global_load_lds_dwordx4 v[216:217], off
	v_lshl_add_u64 v[216:217], v[222:223], 0, s[10:11]
	s_mov_b32 m0, s45
	s_nop 0
	global_load_lds_dwordx4 v[216:217], off
	s_waitcnt vmcnt(8)
	s_waitcnt lgkmcnt(0)
	s_barrier
	s_setprio 1
	s_waitcnt lgkmcnt(0)
	v_mfma_f32_16x16x32_bf16 v[60:63], v[128:131], v[184:187], v[60:63]
	v_mfma_f32_16x16x32_bf16 v[60:63], v[132:135], v[188:191], v[60:63]
	v_mfma_f32_16x16x32_bf16 v[44:47], v[128:131], v[192:195], v[44:47]
	v_mfma_f32_16x16x32_bf16 v[44:47], v[132:135], v[196:199], v[44:47]
	v_mfma_f32_16x16x32_bf16 v[28:31], v[128:131], v[200:203], v[28:31]
	v_mfma_f32_16x16x32_bf16 v[28:31], v[132:135], v[204:207], v[28:31]
	v_mfma_f32_16x16x32_bf16 v[12:15], v[128:131], v[208:211], v[12:15]
	v_mfma_f32_16x16x32_bf16 v[12:15], v[132:135], v[212:215], v[12:15]
	v_mfma_f32_16x16x32_bf16 v[56:59], v[136:139], v[184:187], v[56:59]
	v_mfma_f32_16x16x32_bf16 v[56:59], v[140:143], v[188:191], v[56:59]
	v_mfma_f32_16x16x32_bf16 v[40:43], v[136:139], v[192:195], v[40:43]
	v_mfma_f32_16x16x32_bf16 v[40:43], v[140:143], v[196:199], v[40:43]
	v_mfma_f32_16x16x32_bf16 v[24:27], v[136:139], v[200:203], v[24:27]
	v_mfma_f32_16x16x32_bf16 v[24:27], v[140:143], v[204:207], v[24:27]
	v_mfma_f32_16x16x32_bf16 v[8:11], v[136:139], v[208:211], v[8:11]
	v_mfma_f32_16x16x32_bf16 v[8:11], v[140:143], v[212:215], v[8:11]
	s_setprio 0
	s_setprio 1
	v_mfma_f32_16x16x32_bf16 v[52:55], v[160:163], v[184:187], v[52:55]
	v_mfma_f32_16x16x32_bf16 v[52:55], v[172:175], v[188:191], v[52:55]
	v_mfma_f32_16x16x32_bf16 v[36:39], v[160:163], v[192:195], v[36:39]
	v_mfma_f32_16x16x32_bf16 v[36:39], v[172:175], v[196:199], v[36:39]
	v_mfma_f32_16x16x32_bf16 v[20:23], v[160:163], v[200:203], v[20:23]
	v_mfma_f32_16x16x32_bf16 v[20:23], v[172:175], v[204:207], v[20:23]
	v_mfma_f32_16x16x32_bf16 v[4:7], v[160:163], v[208:211], v[4:7]
	v_mfma_f32_16x16x32_bf16 v[4:7], v[172:175], v[212:215], v[4:7]
	v_mfma_f32_16x16x32_bf16 v[48:51], v[176:179], v[184:187], v[48:51]
	v_mfma_f32_16x16x32_bf16 v[48:51], v[180:183], v[188:191], v[48:51]
	v_mfma_f32_16x16x32_bf16 v[32:35], v[176:179], v[192:195], v[32:35]
	v_mfma_f32_16x16x32_bf16 v[32:35], v[180:183], v[196:199], v[32:35]
	v_mfma_f32_16x16x32_bf16 v[16:19], v[176:179], v[200:203], v[16:19]
	v_mfma_f32_16x16x32_bf16 v[16:19], v[180:183], v[204:207], v[16:19]
	v_mfma_f32_16x16x32_bf16 v[0:3], v[176:179], v[208:211], v[0:3]
	v_mfma_f32_16x16x32_bf16 v[0:3], v[180:183], v[212:215], v[0:3]
	s_setprio 0
	s_barrier
	s_movk_i32 s54, 0x100
	s_andn2_b64 vcc, exec, s[4:5]
	s_mov_b64 s[68:69], -1
	s_mov_b64 s[4:5], 0
	s_cbranch_vccz .LBB0_296
	s_and_b64 vcc, exec, s[12:13]
	s_cbranch_vccz .LBB0_299
	s_barrier
